# gate/up GEMM tile order: M-tile group of the per-XCD sweep 2 -> 4 (4 A-tiles x 8 B-tiles per round per XCD instead of 2 x 16: less data from beyond L2)
# speedup vs baseline: 1.0012x; 1.0012x over previous
.LBB0_153:
	s_and_b32 s5, s2, 7
	s_mul_i32 s6, s5, 0x60
	v_writelane_b32 v245, s6, 5
	s_or_b32 s6, s6, s82
	s_mul_i32 s4, s9, s8
	s_mul_hi_u32 s7, s6, 0x15555556
	s_lshl_b32 s9, s85, 18
	s_lshl_b32 s8, s7, 1
	s_mul_i32 s7, s7, 12
	s_and_b32 s9, s9, 0x3f80000
	s_sub_i32 s6, s6, s7
	v_readlane_b32 s7, v245, 3
	v_writelane_b32 v245, s9, 6
	s_lshl_b32 s9, s85, 7
	s_lshl_b32 s10, s83, 17
	s_bfe_u32 s7, s7, 0x10003
	v_writelane_b32 v245, s10, 7
	s_and_b32 s9, s9, 0xf00
	v_writelane_b32 v245, s9, 8
	s_lshl_b32 s9, s7, 8
	v_writelane_b32 v245, s9, 9
	s_mul_i32 s4, s4, s84
	s_lshl_b32 s19, s7, 19
	v_writelane_b32 v245, s4, 10
	s_lshr_b32 s4, s83, 5
	s_lshl_b32 s9, s83, 1
	v_writelane_b32 v245, s9, 11
	s_cmpk_lt_u32 s83, 0x80
	s_movk_i32 s9, 0xa1
	s_cselect_b32 s9, s9, 0xa0
	v_writelane_b32 v245, s9, 12
	s_cselect_b32 s9, 33, 32
	v_writelane_b32 v245, s9, 13
	s_or_b32 s9, s9, 0x50
	v_writelane_b32 v245, s9, 14
	s_add_i32 s63, 0, 0x10000
	v_readlane_b32 s18, v245, 2
	s_lshl_b32 s9, s18, 5
	v_writelane_b32 v245, s9, 15
	s_lshl_b32 s9, s18, 4
	s_lshl_b32 s10, s18, 3
	s_and_b32 s9, s9, 48
	v_writelane_b32 v245, s9, 16
	s_and_b32 s9, s10, 0x1fffffe0
	v_writelane_b32 v245, s10, 17
	s_addk_i32 s9, 0x400
	v_writelane_b32 v245, s9, 18
	s_mul_i32 s9, s4, 0xc00000
	v_writelane_b32 v245, s9, 19
	s_lshl_b32 s9, s18, 10
	s_add_i32 s10, s63, s9
	s_add_i32 s11, s10, 0x2000
	v_writelane_b32 v245, s11, 20
	s_add_i32 s11, s10, 0x4000
	v_writelane_b32 v245, s11, 21
	v_writelane_b32 v245, s10, 22
	s_addk_i32 s10, 0x6000
	s_add_i32 s64, s9, 0
	v_writelane_b32 v245, s10, 23
	s_add_i32 s9, s64, 0x2000
	v_writelane_b32 v245, s9, 24
	s_lshl_b32 s9, s18, 12
	v_writelane_b32 v245, s9, 25
	s_add_i32 s52, s63, s9
	s_lshl_b32 s9, s18, 2
	s_add_i32 s9, s9, 0
	s_add_i32 s9, s9, 0x18000
	v_writelane_b32 v245, s9, 26
	s_add_i32 s10, s64, 0x4000
	v_writelane_b32 v245, s10, 27
	s_add_i32 s10, s64, 0x6000
	v_writelane_b32 v245, s10, 28
	s_add_i32 s10, s64, 0x8000
	v_writelane_b32 v245, s10, 29
	s_add_i32 s10, s64, 0xa000
	v_writelane_b32 v245, s10, 30
	s_add_i32 s10, s83, 0xffffffb0
	v_writelane_b32 v245, s10, 31
	s_or_b32 s10, s4, 0x100
	v_writelane_b32 v245, s10, 32
	s_lshl_b32 s10, s18, 13
	v_writelane_b32 v245, s10, 33
	s_mul_i32 s10, s18, 0x1c00
	s_add_i32 s65, s64, s10
	s_add_i32 s10, s65, 0x10000
	v_writelane_b32 v245, s10, 34
	s_add_i32 s10, s65, 0x10400
	v_writelane_b32 v245, s10, 35
	s_add_i32 s10, s65, 0x10800
	v_writelane_b32 v245, s10, 36
	s_add_i32 s10, s65, 0x10c00
	v_writelane_b32 v245, s10, 37
	s_add_i32 s10, s65, 0x11000
	v_writelane_b32 v245, s10, 38
	s_add_i32 s10, s65, 0x11400
	v_writelane_b32 v245, s10, 39
	s_add_i32 s10, s65, 0x11800
	v_writelane_b32 v245, s10, 40
	s_add_i32 s10, s65, 0x11c00
	v_writelane_b32 v245, s10, 41
	s_mul_i32 s10, s18, 0xffffe002
	s_add_i32 s10, s65, s10
	v_writelane_b32 v245, s10, 42
	s_mul_i32 s10, s18, 14
	s_and_b32 s10, s10, 14
	s_add_i32 s10, s63, s10
	v_writelane_b32 v245, s10, 43
	s_mulk_i32 s5, 0x160
	s_add_i32 s13, s4, 3
	v_writelane_b32 v245, s5, 44
	s_or_b32 s5, s5, s82
	s_lshl_b32 s14, s13, 6
	s_mul_hi_u32 s11, s5, 0x5d1745e
	s_lshr_b32 s11, s11, 1
	s_and_b32 s33, s14, 0x1c0
	s_add_i32 s14, s4, 4
	s_lshl_b32 s12, s11, 2
	s_mul_i32 s11, s11, 88
	s_lshl_b32 s15, s14, 6
	s_sub_i32 s5, s5, s11
	s_and_b32 s11, s6, 1
	s_and_b32 s46, s15, 0x1c0
	s_add_i32 s15, s4, 5
	s_or_b32 s8, s11, s8
	s_lshl_b32 s16, s15, 6
	v_writelane_b32 v245, s8, 45
	s_lshl_b32 s8, s8, 19
	s_and_b32 s47, s16, 0x1c0
	s_add_i32 s16, s4, 6
	s_add_i32 s53, s4, 1
	v_writelane_b32 v245, s8, 46
	s_add_i32 s8, s4, 2
	s_lshl_b32 s17, s16, 6
	s_add_i32 s4, s4, 7
	s_lshr_b32 s6, s6, 1
	s_and_b32 s48, s17, 0x1c0
	s_lshl_b32 s17, s4, 6
	v_writelane_b32 v245, s6, 47
	s_lshl_b32 s6, s6, 19
	s_and_b32 s49, s17, 0x1c0
	s_bfe_i32 s17, s53, 0x10002
	v_writelane_b32 v245, s6, 48
	s_lshl_b32 s11, s8, 6
	s_addk_i32 s17, 0xa1
	s_bfe_i32 s8, s8, 0x10002
	v_writelane_b32 v245, s17, 49
	s_addk_i32 s8, 0xa1
	v_writelane_b32 v245, s8, 50
	s_bfe_i32 s8, s13, 0x10002
	s_addk_i32 s8, 0xa1
	v_writelane_b32 v245, s8, 51
	s_bfe_i32 s8, s14, 0x10002
	s_addk_i32 s8, 0xa1
	v_writelane_b32 v245, s8, 52
	s_bfe_i32 s8, s15, 0x10002
	s_addk_i32 s8, 0xa1
	s_or_b32 s10, s3, s82
	v_writelane_b32 v245, s8, 53
	s_bfe_i32 s8, s16, 0x10002
	s_lshr_b32 s10, s10, 2
	s_addk_i32 s8, 0xa1
	s_bfe_i32 s4, s4, 0x10002
	s_and_b32 s10, s10, 62
	v_writelane_b32 v245, s8, 54
	s_addk_i32 s4, 0xa1
	v_writelane_b32 v245, s4, 55
	s_or_b32 s4, s7, s10
	s_bfe_u32 s2, s2, 0x20004
	v_writelane_b32 v245, s4, 56
	s_lshl_b32 s4, s4, 19
	v_writelane_b32 v245, s4, 57
	s_lshl_b32 s4, s2, 19
	v_writelane_b32 v245, s4, 58
	v_writelane_b32 v245, s2, 59
	s_lshl_b32 s2, s2, 8
	v_writelane_b32 v245, s2, 60
	s_and_b32 s2, s5, 3
	s_or_b32 s2, s2, s12
	s_lshr_b32 s4, s5, 2
	v_writelane_b32 v245, s2, 61
	s_lshl_b32 s2, s2, 19
	v_writelane_b32 v245, s2, 62
	s_lshl_b32 s2, s4, 19
	s_lshl_b32 s6, s53, 6
	v_writelane_b32 v244, s2, 0
	s_lshl_b32 s2, s83, 7
	v_writelane_b32 v244, s2, 1
	s_or_b32 s2, s19, 0x540080
	v_writelane_b32 v244, s2, 2
	s_add_i32 s2, s82, s83
	s_lshl_b32 s2, s2, 18
	s_lshr_b32 s9, s83, 2
	s_and_b32 s6, s6, 0x1c0
	s_and_b32 s11, s11, 0x1c0
	s_and_b32 s2, s2, 0x7f80000
	s_add_u32 s2, s2, 0x7200100
	v_writelane_b32 v244, s2, 3
	s_addc_u32 s2, 0, 0
	v_writelane_b32 v244, s2, 4
	s_lshl_b32 s2, s18, 7
	s_add_i32 s82, s82, s3
	v_writelane_b32 v244, s2, 5
	s_bfe_u32 s2, s82, 0x50003
	s_lshl_b32 s3, s2, 20
	s_or_b32 s3, s3, s19
	v_writelane_b32 v244, s19, 6
	s_add_u32 s3, s3, 0xb240080
	s_mul_i32 s2, s2, 0x2c0000
	s_mul_i32 s7, s7, 0x160000
	v_writelane_b32 v244, s3, 7
	s_addc_u32 s3, 0, 0
	s_add_i32 s2, s2, s7
	v_writelane_b32 v244, s3, 8
	s_add_u32 s2, s2, 0x132b0080
	v_writelane_b32 v244, s2, 9
	s_addc_u32 s2, 0, 0
	v_writelane_b32 v244, s2, 10
	s_lshl_b32 s2, s9, 2
	v_writelane_b32 v244, s2, 11
	s_lshl_b32 s2, s6, 2
	v_writelane_b32 v244, s2, 12
	s_lshl_b32 s2, s11, 2
	v_writelane_b32 v244, s2, 13
	s_lshl_b32 s2, s33, 2
	v_writelane_b32 v244, s2, 14
	s_lshl_b32 s2, s46, 2
	v_writelane_b32 v244, s2, 15
	s_lshl_b32 s2, s47, 2
	v_writelane_b32 v244, s2, 16
	s_lshl_b32 s2, s48, 2
	v_writelane_b32 v244, s2, 17
	s_lshl_b32 s2, s49, 2
	v_writelane_b32 v244, s2, 18
	s_add_i32 s2, 0, 0x24020
	v_writelane_b32 v244, s2, 19
	s_add_i32 s2, 0, 0x24024
	v_writelane_b32 v244, s2, 20
	s_add_i32 s2, 0, 0x18010
	v_writelane_b32 v244, s2, 21
	s_mov_b64 s[2:3], 0
	v_writelane_b32 v244, s2, 22
	s_mov_b32 s14, 2.0
	s_mov_b32 s16, 0x41000000
	v_writelane_b32 v244, s3, 23
	s_mov_b32 s18, 0x41200000
	s_mov_b32 s20, 0x41800000
	s_mov_b32 s22, 0x41900000
	s_mov_b32 s24, 0x41c00000
	s_mov_b32 s26, 0x41d00000
	s_mov_b32 s28, 0x42680000
	s_mov_b32 s30, 0x42600000
	s_mov_b32 s34, 0x42480000
	s_mov_b32 s36, 0x42400000
	s_mov_b32 s38, 0x42280000
	s_mov_b32 s40, 0x42200000
	s_mov_b32 s42, 0x42080000
	s_mov_b32 s44, 0x42000000
	v_writelane_b32 v244, s76, 24
	v_writelane_b32 v245, s4, 63
	v_mov_b32_e32 v1, 0
	v_mov_b32_e32 v227, 0x1000
	v_mov_b32_e32 v228, 0x2000
	v_mov_b32_e32 v229, 0x7000
	v_mov_b32_e32 v230, 1
	v_mov_b32_e32 v231, 0x3f4ccccd
	v_mov_b32_e32 v232, 0x260
	s_mov_b32 s15, 0x40400000
	s_mov_b32 s17, 0x41100000
	s_mov_b32 s19, 0x41300000
	s_mov_b32 s21, 0x41880000
	s_mov_b32 s23, 0x41980000
	s_mov_b32 s25, 0x41c80000
	s_mov_b32 s27, 0x41d80000
	s_mov_b32 s29, 0x426c0000
	s_mov_b32 s31, 0x42640000
	s_mov_b32 s35, 0x424c0000
	s_mov_b32 s37, 0x42440000
	s_mov_b32 s39, 0x422c0000
	s_mov_b32 s41, 0x42240000
	s_mov_b32 s43, 0x420c0000
	s_mov_b32 s45, 0x42040000
	v_mov_b32_e32 v233, 0x3727c5ac
	v_mov_b32_e32 v234, 0x7f800000
	v_mov_b32_e32 v235, 0x3fb8aa3b
	v_mov_b32_e32 v236, 0xa0
	v_mov_b32_e32 v237, 0xa1
	v_mov_b64_e32 v[190:191], 0x1e8481
	v_mov_b32_e32 v238, 0x7fc00000
	s_movk_i32 s48, 0xc00
	s_movk_i32 s49, 0x7fff
	s_add_i32 s90, 0, 0x18100
	s_movk_i32 s62, 0x1600
	s_mov_b32 s46, 0
	s_mov_b32 s47, 0
	s_mov_b64 s[4:5], -1
	s_mov_b64 s[50:51], 0x80
	s_mov_b32 s54, 0x3c800000
	s_mov_b32 s66, 0x3fb504f3
	v_writelane_b32 v244, s77, 25
	v_writelane_b32 v244, s90, 26
	s_branch .LBB0_157

.LBB0_880:
	s_add_i32 s88, s89, 1
	s_cmp_lt_u32 s89, 10
	s_cselect_b64 s[12:13], -1, 0
	s_cmp_gt_u32 s89, 9
	s_cbranch_scc1 .LBB0_882
	s_lshl_b32 s8, s88, 8
	v_readlane_b32 s9, v245, 3
	s_or_b32 s8, s8, s9
	s_lshr_b32 s8, s8, 3
	v_readlane_b32 s9, v245, 44
	s_add_i32 s8, s8, s9
	s_mul_hi_u32 s9, s8, 0xba2e8ba3
	s_lshr_b32 s9, s9, 6
	s_lshl_b32 s55, s9, 2
	s_mul_i32 s9, s9, 88
	s_sub_i32 s9, s8, s9
	s_and_b32 s8, s9, 3
	s_or_b32 s8, s8, s55
	s_lshr_b32 s74, s9, 2
